# v17_barfast
# speedup vs baseline: 1.0049x; 1.0049x over previous
; __device__ __forceinline__ unsigned xb_ld(unsigned* p)              { return __hip_atomic_load(p, __ATOMIC_RELAXED, __HIP_MEMORY_SCOPE_AGENT); }
; __device__ __forceinline__ unsigned xb_add(unsigned* p, unsigned v) { return __hip_atomic_fetch_add(p, v, __ATOMIC_RELAXED, __HIP_MEMORY_SCOPE_AGENT); }
; #define XB_SPIN(cond, bar) do { unsigned _sp = 0; while (cond) { __builtin_amdgcn_s_sleep(1); \
;     if ((++_sp & 255u) == 0u) { if (xb_ld(&(bar)[XB_TMO])) break; if (_sp > XB_SPIN_CAP) { atomicAdd(&(bar)[XB_TMO], 1u); break; } } } } while (0)
; __device__ __forceinline__ void xcd_barrier(const XcdBarrier& b, int wv) {
;     ...
;     const unsigned old = xb_add(&bar[XB_XSUB(b.x)], 1u);
;     const unsigned gen = old / b.nloc;
;     if (old + 1u == (gen + 1u) * b.nloc) {
;       __builtin_amdgcn_fence(__ATOMIC_RELEASE, "agent");
;       asm volatile("s_waitcnt vmcnt(0)" ::: "memory");
;       const unsigned og = xb_add(&bar[XB_TOP], 1u);
;       const unsigned tg = og / b.nx;
;       if (og + 1u == (tg + 1u) * b.nx) xb_add(&bar[XB_TOPGEN], 1u);
;       else XB_SPIN(xb_ld(&bar[XB_TOPGEN]) == tg, bar);
;       __builtin_amdgcn_fence(__ATOMIC_ACQUIRE, "agent");
;       xb_add(&bar[XB_XGEN(b.x)], 1u);
;     } else {
;       XB_SPIN(xb_ld(&bar[XB_XGEN(b.x)]) == gen, bar);
.LBB0_144:
	s_or_b64 exec, exec, s[10:11]
	v_cvt_f32_u32_e32 v4, s84
	s_waitcnt vmcnt(0)
	v_readfirstlane_b32 s5, v3
	s_sub_i32 s8, 0, s84
	s_mov_b32 s11, 0
	v_rcp_iflag_f32_e32 v4, v4
	s_nop 0
	v_mul_f32_e32 v3, 0x4f7ffffe, v4
	v_cvt_u32_f32_e32 v3, v3
	v_add_u32_e32 v4, s5, v2
	v_mul_lo_u32 v2, s8, v3
	v_mul_hi_u32 v2, v3, v2
	v_add_u32_e32 v2, v3, v2
	v_mul_hi_u32 v2, v4, v2
	v_mul_lo_u32 v3, v2, s84
	v_sub_u32_e32 v3, v4, v3
	v_add_u32_e32 v5, 1, v2
	v_cmp_le_u32_e32 vcc, s84, v3
	s_nop 1
	v_cndmask_b32_e32 v2, v2, v5, vcc
	v_subrev_u32_e32 v5, s84, v3
	v_cndmask_b32_e32 v3, v3, v5, vcc
	v_add_u32_e32 v5, 1, v2
	v_cmp_le_u32_e32 vcc, s84, v3
	v_add_u32_e32 v3, 1, v4
	s_nop 0
	v_cndmask_b32_e32 v2, v2, v5, vcc
	v_mul_lo_u32 v4, s84, v2
	v_add_u32_e32 v4, s84, v4
	v_cmp_ne_u32_e32 vcc, v3, v4
	s_and_saveexec_b64 s[8:9], vcc
	s_xor_b64 s[8:9], exec, s[8:9]
	s_cbranch_execz .LBB0_158
	s_movk_i32 s10, 0xd40
	s_lshl_b64 s[10:11], s[10:11], 2
	s_add_u32 s18, s34, s10
	s_addc_u32 s19, s35, s11
	v_mov_b32_e32 v3, 0
	v_mov_b32_e32 v2, 0
	global_load_dword v4, v3, s[18:19] sc1
	s_waitcnt vmcnt(0)
	v_cmp_eq_u32_e32 vcc, v4, v2
	s_and_saveexec_b64 s[10:11], vcc
	s_cbranch_execz .LBB0_157
	s_add_u32 s16, s40, 0x3eaf0200
	s_addc_u32 s17, s41, 0
	s_mov_b32 s5, 1
	s_mov_b64 s[20:21], 0
	s_branch .LBB0_148

; __device__ __forceinline__ unsigned xb_ld(unsigned* p)              { return __hip_atomic_load(p, __ATOMIC_RELAXED, __HIP_MEMORY_SCOPE_AGENT); }
; __device__ __forceinline__ unsigned xb_add(unsigned* p, unsigned v) { return __hip_atomic_fetch_add(p, v, __ATOMIC_RELAXED, __HIP_MEMORY_SCOPE_AGENT); }
; #define XB_SPIN(cond, bar) do { unsigned _sp = 0; while (cond) { __builtin_amdgcn_s_sleep(1); \
;     if ((++_sp & 255u) == 0u) { if (xb_ld(&(bar)[XB_TMO])) break; if (_sp > XB_SPIN_CAP) { atomicAdd(&(bar)[XB_TMO], 1u); break; } } } } while (0)
; __device__ __forceinline__ void xcd_barrier(const XcdBarrier& b, int wv) {
;     ...
;     const unsigned old = xb_add(&bar[XB_XSUB(b.x)], 1u);
;     const unsigned gen = old / b.nloc;
;     if (old + 1u == (gen + 1u) * b.nloc) {
;       __builtin_amdgcn_fence(__ATOMIC_RELEASE, "agent");
;       asm volatile("s_waitcnt vmcnt(0)" ::: "memory");
;       const unsigned og = xb_add(&bar[XB_TOP], 1u);
;       const unsigned tg = og / b.nx;
;       if (og + 1u == (tg + 1u) * b.nx) xb_add(&bar[XB_TOPGEN], 1u);
;       else XB_SPIN(xb_ld(&bar[XB_TOPGEN]) == tg, bar);
;       __builtin_amdgcn_fence(__ATOMIC_ACQUIRE, "agent");
;       xb_add(&bar[XB_XGEN(b.x)], 1u);
;     } else {
;       XB_SPIN(xb_ld(&bar[XB_XGEN(b.x)]) == gen, bar);
.LBB0_196:
	s_or_b64 exec, exec, s[6:7]
	v_cvt_f32_u32_e32 v2, s84
	s_waitcnt vmcnt(0)
	v_readfirstlane_b32 s4, v1
	s_sub_i32 s5, 0, s84
	s_mov_b32 s7, 0
	v_rcp_iflag_f32_e32 v2, v2
	s_nop 0
	v_mul_f32_e32 v1, 0x4f7ffffe, v2
	v_cvt_u32_f32_e32 v1, v1
	v_add_u32_e32 v2, s4, v0
	v_mul_lo_u32 v0, s5, v1
	v_mul_hi_u32 v0, v1, v0
	v_add_u32_e32 v0, v1, v0
	v_mul_hi_u32 v0, v2, v0
	v_mul_lo_u32 v1, v0, s84
	v_sub_u32_e32 v1, v2, v1
	v_add_u32_e32 v3, 1, v0
	v_cmp_le_u32_e32 vcc, s84, v1
	s_nop 1
	v_cndmask_b32_e32 v0, v0, v3, vcc
	v_subrev_u32_e32 v3, s84, v1
	v_cndmask_b32_e32 v1, v1, v3, vcc
	v_add_u32_e32 v3, 1, v0
	v_cmp_le_u32_e32 vcc, s84, v1
	v_add_u32_e32 v1, 1, v2
	s_nop 0
	v_cndmask_b32_e32 v0, v0, v3, vcc
	v_mul_lo_u32 v2, s84, v0
	v_add_u32_e32 v2, s84, v2
	v_cmp_ne_u32_e32 vcc, v1, v2
	s_and_saveexec_b64 s[4:5], vcc
	s_xor_b64 s[4:5], exec, s[4:5]
	s_cbranch_execz .LBB0_210
	s_movk_i32 s6, 0xd40
	s_lshl_b64 s[6:7], s[6:7], 2
	s_add_u32 s10, s34, s6
	s_addc_u32 s11, s35, s7
	v_mov_b32_e32 v1, 0
	v_mov_b32_e32 v0, 1
	global_load_dword v2, v1, s[10:11] sc1
	s_waitcnt vmcnt(0)
	v_cmp_eq_u32_e32 vcc, v2, v0
	s_and_saveexec_b64 s[6:7], vcc
	s_cbranch_execz .LBB0_209
	s_add_u32 s8, s40, 0x3eaf0200
	s_addc_u32 s9, s41, 0
	s_mov_b32 s26, 1
	s_mov_b64 s[12:13], 0
	s_branch .LBB0_200

; __device__ __forceinline__ unsigned xb_ld(unsigned* p)              { return __hip_atomic_load(p, __ATOMIC_RELAXED, __HIP_MEMORY_SCOPE_AGENT); }
; __device__ __forceinline__ unsigned xb_add(unsigned* p, unsigned v) { return __hip_atomic_fetch_add(p, v, __ATOMIC_RELAXED, __HIP_MEMORY_SCOPE_AGENT); }
; #define XB_SPIN(cond, bar) do { unsigned _sp = 0; while (cond) { __builtin_amdgcn_s_sleep(1); \
;     if ((++_sp & 255u) == 0u) { if (xb_ld(&(bar)[XB_TMO])) break; if (_sp > XB_SPIN_CAP) { atomicAdd(&(bar)[XB_TMO], 1u); break; } } } } while (0)
; __device__ __forceinline__ void xcd_barrier(const XcdBarrier& b, int wv) {
;     ...
;     const unsigned old = xb_add(&bar[XB_XSUB(b.x)], 1u);
;     const unsigned gen = old / b.nloc;
;     if (old + 1u == (gen + 1u) * b.nloc) {
;       __builtin_amdgcn_fence(__ATOMIC_RELEASE, "agent");
;       asm volatile("s_waitcnt vmcnt(0)" ::: "memory");
;       const unsigned og = xb_add(&bar[XB_TOP], 1u);
;       const unsigned tg = og / b.nx;
;       if (og + 1u == (tg + 1u) * b.nx) xb_add(&bar[XB_TOPGEN], 1u);
;       else XB_SPIN(xb_ld(&bar[XB_TOPGEN]) == tg, bar);
;       __builtin_amdgcn_fence(__ATOMIC_ACQUIRE, "agent");
;       xb_add(&bar[XB_XGEN(b.x)], 1u);
;     } else {
;       XB_SPIN(xb_ld(&bar[XB_XGEN(b.x)]) == gen, bar);
.LBB0_236:
	s_or_b64 exec, exec, s[6:7]
	v_cvt_f32_u32_e32 v2, s84
	s_waitcnt vmcnt(0)
	v_readfirstlane_b32 s4, v1
	s_sub_i32 s5, 0, s84
	s_mov_b32 s7, 0
	v_rcp_iflag_f32_e32 v2, v2
	s_nop 0
	v_mul_f32_e32 v1, 0x4f7ffffe, v2
	v_cvt_u32_f32_e32 v1, v1
	v_add_u32_e32 v2, s4, v0
	v_mul_lo_u32 v0, s5, v1
	v_mul_hi_u32 v0, v1, v0
	v_add_u32_e32 v0, v1, v0
	v_mul_hi_u32 v0, v2, v0
	v_mul_lo_u32 v1, v0, s84
	v_sub_u32_e32 v1, v2, v1
	v_add_u32_e32 v3, 1, v0
	v_cmp_le_u32_e32 vcc, s84, v1
	s_nop 1
	v_cndmask_b32_e32 v0, v0, v3, vcc
	v_subrev_u32_e32 v3, s84, v1
	v_cndmask_b32_e32 v1, v1, v3, vcc
	v_add_u32_e32 v3, 1, v0
	v_cmp_le_u32_e32 vcc, s84, v1
	v_add_u32_e32 v1, 1, v2
	s_nop 0
	v_cndmask_b32_e32 v0, v0, v3, vcc
	v_mul_lo_u32 v2, s84, v0
	v_add_u32_e32 v2, s84, v2
	v_cmp_ne_u32_e32 vcc, v1, v2
	s_and_saveexec_b64 s[4:5], vcc
	s_xor_b64 s[4:5], exec, s[4:5]
	s_cbranch_execz .LBB0_250
	s_movk_i32 s6, 0xd40
	s_lshl_b64 s[6:7], s[6:7], 2
	s_add_u32 s10, s34, s6
	s_addc_u32 s11, s35, s7
	v_mov_b32_e32 v1, 0
	v_mov_b32_e32 v0, 2
	global_load_dword v2, v1, s[10:11] sc1
	s_waitcnt vmcnt(0)
	v_cmp_eq_u32_e32 vcc, v2, v0
	s_and_saveexec_b64 s[6:7], vcc
	s_cbranch_execz .LBB0_249
	s_add_u32 s8, s40, 0x3eaf0200
	s_addc_u32 s9, s41, 0
	s_mov_b32 s26, 1
	s_mov_b64 s[12:13], 0
	s_branch .LBB0_240

; __device__ __forceinline__ unsigned xb_ld(unsigned* p)              { return __hip_atomic_load(p, __ATOMIC_RELAXED, __HIP_MEMORY_SCOPE_AGENT); }
; __device__ __forceinline__ unsigned xb_add(unsigned* p, unsigned v) { return __hip_atomic_fetch_add(p, v, __ATOMIC_RELAXED, __HIP_MEMORY_SCOPE_AGENT); }
; #define XB_SPIN(cond, bar) do { unsigned _sp = 0; while (cond) { __builtin_amdgcn_s_sleep(1); \
;     if ((++_sp & 255u) == 0u) { if (xb_ld(&(bar)[XB_TMO])) break; if (_sp > XB_SPIN_CAP) { atomicAdd(&(bar)[XB_TMO], 1u); break; } } } } while (0)
; __device__ __forceinline__ void xcd_barrier(const XcdBarrier& b, int wv) {
;     ...
;     const unsigned old = xb_add(&bar[XB_XSUB(b.x)], 1u);
;     const unsigned gen = old / b.nloc;
;     if (old + 1u == (gen + 1u) * b.nloc) {
;       __builtin_amdgcn_fence(__ATOMIC_RELEASE, "agent");
;       asm volatile("s_waitcnt vmcnt(0)" ::: "memory");
;       const unsigned og = xb_add(&bar[XB_TOP], 1u);
;       const unsigned tg = og / b.nx;
;       if (og + 1u == (tg + 1u) * b.nx) xb_add(&bar[XB_TOPGEN], 1u);
;       else XB_SPIN(xb_ld(&bar[XB_TOPGEN]) == tg, bar);
;       __builtin_amdgcn_fence(__ATOMIC_ACQUIRE, "agent");
;       xb_add(&bar[XB_XGEN(b.x)], 1u);
;     } else {
;       XB_SPIN(xb_ld(&bar[XB_XGEN(b.x)]) == gen, bar);
.LBB0_283:
	s_or_b64 exec, exec, s[6:7]
	v_cvt_f32_u32_e32 v2, s84
	s_waitcnt vmcnt(0)
	v_readfirstlane_b32 s4, v1
	s_sub_i32 s5, 0, s84
	s_mov_b32 s7, 0
	v_rcp_iflag_f32_e32 v2, v2
	s_nop 0
	v_mul_f32_e32 v1, 0x4f7ffffe, v2
	v_cvt_u32_f32_e32 v1, v1
	v_add_u32_e32 v2, s4, v0
	v_mul_lo_u32 v0, s5, v1
	v_mul_hi_u32 v0, v1, v0
	v_add_u32_e32 v0, v1, v0
	v_mul_hi_u32 v0, v2, v0
	v_mul_lo_u32 v1, v0, s84
	v_sub_u32_e32 v1, v2, v1
	v_add_u32_e32 v3, 1, v0
	v_cmp_le_u32_e32 vcc, s84, v1
	s_nop 1
	v_cndmask_b32_e32 v0, v0, v3, vcc
	v_subrev_u32_e32 v3, s84, v1
	v_cndmask_b32_e32 v1, v1, v3, vcc
	v_add_u32_e32 v3, 1, v0
	v_cmp_le_u32_e32 vcc, s84, v1
	v_add_u32_e32 v1, 1, v2
	s_nop 0
	v_cndmask_b32_e32 v0, v0, v3, vcc
	v_mul_lo_u32 v2, s84, v0
	v_add_u32_e32 v2, s84, v2
	v_cmp_ne_u32_e32 vcc, v1, v2
	s_and_saveexec_b64 s[4:5], vcc
	s_xor_b64 s[4:5], exec, s[4:5]
	s_cbranch_execz .LBB0_297
	s_movk_i32 s6, 0xd40
	s_lshl_b64 s[6:7], s[6:7], 2
	s_add_u32 s10, s34, s6
	s_addc_u32 s11, s35, s7
	v_mov_b32_e32 v1, 0
	v_mov_b32_e32 v0, 3
	global_load_dword v2, v1, s[10:11] sc1
	s_waitcnt vmcnt(0)
	v_cmp_eq_u32_e32 vcc, v2, v0
	s_and_saveexec_b64 s[6:7], vcc
	s_cbranch_execz .LBB0_296
	s_add_u32 s8, s40, 0x3eaf0200
	s_addc_u32 s9, s41, 0
	s_mov_b32 s26, 1
	s_mov_b64 s[12:13], 0
	s_branch .LBB0_287

; __device__ __forceinline__ unsigned xb_ld(unsigned* p)              { return __hip_atomic_load(p, __ATOMIC_RELAXED, __HIP_MEMORY_SCOPE_AGENT); }
; __device__ __forceinline__ unsigned xb_add(unsigned* p, unsigned v) { return __hip_atomic_fetch_add(p, v, __ATOMIC_RELAXED, __HIP_MEMORY_SCOPE_AGENT); }
; #define XB_SPIN(cond, bar) do { unsigned _sp = 0; while (cond) { __builtin_amdgcn_s_sleep(1); \
;     if ((++_sp & 255u) == 0u) { if (xb_ld(&(bar)[XB_TMO])) break; if (_sp > XB_SPIN_CAP) { atomicAdd(&(bar)[XB_TMO], 1u); break; } } } } while (0)
; __device__ __forceinline__ void xcd_barrier(const XcdBarrier& b, int wv) {
;     ...
;     const unsigned old = xb_add(&bar[XB_XSUB(b.x)], 1u);
;     const unsigned gen = old / b.nloc;
;     if (old + 1u == (gen + 1u) * b.nloc) {
;       __builtin_amdgcn_fence(__ATOMIC_RELEASE, "agent");
;       asm volatile("s_waitcnt vmcnt(0)" ::: "memory");
;       const unsigned og = xb_add(&bar[XB_TOP], 1u);
;       const unsigned tg = og / b.nx;
;       if (og + 1u == (tg + 1u) * b.nx) xb_add(&bar[XB_TOPGEN], 1u);
;       else XB_SPIN(xb_ld(&bar[XB_TOPGEN]) == tg, bar);
;       __builtin_amdgcn_fence(__ATOMIC_ACQUIRE, "agent");
;       xb_add(&bar[XB_XGEN(b.x)], 1u);
;     } else {
;       XB_SPIN(xb_ld(&bar[XB_XGEN(b.x)]) == gen, bar);
.LBB0_330:
	s_or_b64 exec, exec, s[6:7]
	v_cvt_f32_u32_e32 v2, s84
	s_waitcnt vmcnt(0)
	v_readfirstlane_b32 s4, v1
	s_sub_i32 s5, 0, s84
	s_mov_b32 s7, 0
	v_rcp_iflag_f32_e32 v2, v2
	s_nop 0
	v_mul_f32_e32 v1, 0x4f7ffffe, v2
	v_cvt_u32_f32_e32 v1, v1
	v_add_u32_e32 v2, s4, v0
	v_mul_lo_u32 v0, s5, v1
	v_mul_hi_u32 v0, v1, v0
	v_add_u32_e32 v0, v1, v0
	v_mul_hi_u32 v0, v2, v0
	v_mul_lo_u32 v1, v0, s84
	v_sub_u32_e32 v1, v2, v1
	v_add_u32_e32 v3, 1, v0
	v_cmp_le_u32_e32 vcc, s84, v1
	s_nop 1
	v_cndmask_b32_e32 v0, v0, v3, vcc
	v_subrev_u32_e32 v3, s84, v1
	v_cndmask_b32_e32 v1, v1, v3, vcc
	v_add_u32_e32 v3, 1, v0
	v_cmp_le_u32_e32 vcc, s84, v1
	v_add_u32_e32 v1, 1, v2
	s_nop 0
	v_cndmask_b32_e32 v0, v0, v3, vcc
	v_mul_lo_u32 v2, s84, v0
	v_add_u32_e32 v2, s84, v2
	v_cmp_ne_u32_e32 vcc, v1, v2
	s_and_saveexec_b64 s[4:5], vcc
	s_xor_b64 s[4:5], exec, s[4:5]
	s_cbranch_execz .LBB0_344
	s_movk_i32 s6, 0xd40
	s_lshl_b64 s[6:7], s[6:7], 2
	s_add_u32 s10, s34, s6
	s_addc_u32 s11, s35, s7
	v_mov_b32_e32 v1, 0
	v_mov_b32_e32 v0, 4
	global_load_dword v2, v1, s[10:11] sc1
	s_waitcnt vmcnt(0)
	v_cmp_eq_u32_e32 vcc, v2, v0
	s_and_saveexec_b64 s[6:7], vcc
	s_cbranch_execz .LBB0_343
	s_add_u32 s8, s40, 0x3eaf0200
	s_addc_u32 s9, s41, 0
	s_mov_b32 s26, 1
	s_mov_b64 s[12:13], 0
	s_branch .LBB0_334

; __device__ __forceinline__ unsigned xb_ld(unsigned* p)              { return __hip_atomic_load(p, __ATOMIC_RELAXED, __HIP_MEMORY_SCOPE_AGENT); }
; __device__ __forceinline__ unsigned xb_add(unsigned* p, unsigned v) { return __hip_atomic_fetch_add(p, v, __ATOMIC_RELAXED, __HIP_MEMORY_SCOPE_AGENT); }
; #define XB_SPIN(cond, bar) do { unsigned _sp = 0; while (cond) { __builtin_amdgcn_s_sleep(1); \
;     if ((++_sp & 255u) == 0u) { if (xb_ld(&(bar)[XB_TMO])) break; if (_sp > XB_SPIN_CAP) { atomicAdd(&(bar)[XB_TMO], 1u); break; } } } } while (0)
; __device__ __forceinline__ void xcd_barrier(const XcdBarrier& b, int wv) {
;     ...
;     const unsigned old = xb_add(&bar[XB_XSUB(b.x)], 1u);
;     const unsigned gen = old / b.nloc;
;     if (old + 1u == (gen + 1u) * b.nloc) {
;       __builtin_amdgcn_fence(__ATOMIC_RELEASE, "agent");
;       asm volatile("s_waitcnt vmcnt(0)" ::: "memory");
;       const unsigned og = xb_add(&bar[XB_TOP], 1u);
;       const unsigned tg = og / b.nx;
;       if (og + 1u == (tg + 1u) * b.nx) xb_add(&bar[XB_TOPGEN], 1u);
;       else XB_SPIN(xb_ld(&bar[XB_TOPGEN]) == tg, bar);
;       __builtin_amdgcn_fence(__ATOMIC_ACQUIRE, "agent");
;       xb_add(&bar[XB_XGEN(b.x)], 1u);
;     } else {
;       XB_SPIN(xb_ld(&bar[XB_XGEN(b.x)]) == gen, bar);
.LBB0_370:
	s_or_b64 exec, exec, s[6:7]
	v_cvt_f32_u32_e32 v2, s84
	s_waitcnt vmcnt(0)
	v_readfirstlane_b32 s4, v1
	s_sub_i32 s5, 0, s84
	s_mov_b32 s7, 0
	v_rcp_iflag_f32_e32 v2, v2
	s_nop 0
	v_mul_f32_e32 v1, 0x4f7ffffe, v2
	v_cvt_u32_f32_e32 v1, v1
	v_add_u32_e32 v2, s4, v0
	v_mul_lo_u32 v0, s5, v1
	v_mul_hi_u32 v0, v1, v0
	v_add_u32_e32 v0, v1, v0
	v_mul_hi_u32 v0, v2, v0
	v_mul_lo_u32 v1, v0, s84
	v_sub_u32_e32 v1, v2, v1
	v_add_u32_e32 v3, 1, v0
	v_cmp_le_u32_e32 vcc, s84, v1
	s_nop 1
	v_cndmask_b32_e32 v0, v0, v3, vcc
	v_subrev_u32_e32 v3, s84, v1
	v_cndmask_b32_e32 v1, v1, v3, vcc
	v_add_u32_e32 v3, 1, v0
	v_cmp_le_u32_e32 vcc, s84, v1
	v_add_u32_e32 v1, 1, v2
	s_nop 0
	v_cndmask_b32_e32 v0, v0, v3, vcc
	v_mul_lo_u32 v2, s84, v0
	v_add_u32_e32 v2, s84, v2
	v_cmp_ne_u32_e32 vcc, v1, v2
	s_and_saveexec_b64 s[4:5], vcc
	s_xor_b64 s[4:5], exec, s[4:5]
	s_cbranch_execz .LBB0_384
	s_movk_i32 s6, 0xd40
	s_lshl_b64 s[6:7], s[6:7], 2
	s_add_u32 s10, s34, s6
	s_addc_u32 s11, s35, s7
	v_mov_b32_e32 v1, 0
	v_mov_b32_e32 v0, 5
	global_load_dword v2, v1, s[10:11] sc1
	s_waitcnt vmcnt(0)
	v_cmp_eq_u32_e32 vcc, v2, v0
	s_and_saveexec_b64 s[6:7], vcc
	s_cbranch_execz .LBB0_383
	s_add_u32 s8, s40, 0x3eaf0200
	s_addc_u32 s9, s41, 0
	s_mov_b32 s26, 1
	s_mov_b64 s[12:13], 0
	s_branch .LBB0_374

; __device__ __forceinline__ unsigned xb_ld(unsigned* p)              { return __hip_atomic_load(p, __ATOMIC_RELAXED, __HIP_MEMORY_SCOPE_AGENT); }
; __device__ __forceinline__ unsigned xb_add(unsigned* p, unsigned v) { return __hip_atomic_fetch_add(p, v, __ATOMIC_RELAXED, __HIP_MEMORY_SCOPE_AGENT); }
; #define XB_SPIN(cond, bar) do { unsigned _sp = 0; while (cond) { __builtin_amdgcn_s_sleep(1); \
;     if ((++_sp & 255u) == 0u) { if (xb_ld(&(bar)[XB_TMO])) break; if (_sp > XB_SPIN_CAP) { atomicAdd(&(bar)[XB_TMO], 1u); break; } } } } while (0)
; __device__ __forceinline__ void xcd_barrier(const XcdBarrier& b, int wv) {
;     ...
;     const unsigned old = xb_add(&bar[XB_XSUB(b.x)], 1u);
;     const unsigned gen = old / b.nloc;
;     if (old + 1u == (gen + 1u) * b.nloc) {
;       __builtin_amdgcn_fence(__ATOMIC_RELEASE, "agent");
;       asm volatile("s_waitcnt vmcnt(0)" ::: "memory");
;       const unsigned og = xb_add(&bar[XB_TOP], 1u);
;       const unsigned tg = og / b.nx;
;       if (og + 1u == (tg + 1u) * b.nx) xb_add(&bar[XB_TOPGEN], 1u);
;       else XB_SPIN(xb_ld(&bar[XB_TOPGEN]) == tg, bar);
;       __builtin_amdgcn_fence(__ATOMIC_ACQUIRE, "agent");
;       xb_add(&bar[XB_XGEN(b.x)], 1u);
;     } else {
;       XB_SPIN(xb_ld(&bar[XB_XGEN(b.x)]) == gen, bar);
.LBB0_417:
	s_or_b64 exec, exec, s[6:7]
	v_cvt_f32_u32_e32 v2, s84
	s_waitcnt vmcnt(0)
	v_readfirstlane_b32 s4, v1
	s_sub_i32 s5, 0, s84
	s_mov_b32 s7, 0
	v_rcp_iflag_f32_e32 v2, v2
	s_nop 0
	v_mul_f32_e32 v1, 0x4f7ffffe, v2
	v_cvt_u32_f32_e32 v1, v1
	v_add_u32_e32 v2, s4, v0
	v_mul_lo_u32 v0, s5, v1
	v_mul_hi_u32 v0, v1, v0
	v_add_u32_e32 v0, v1, v0
	v_mul_hi_u32 v0, v2, v0
	v_mul_lo_u32 v1, v0, s84
	v_sub_u32_e32 v1, v2, v1
	v_add_u32_e32 v3, 1, v0
	v_cmp_le_u32_e32 vcc, s84, v1
	s_nop 1
	v_cndmask_b32_e32 v0, v0, v3, vcc
	v_subrev_u32_e32 v3, s84, v1
	v_cndmask_b32_e32 v1, v1, v3, vcc
	v_add_u32_e32 v3, 1, v0
	v_cmp_le_u32_e32 vcc, s84, v1
	v_add_u32_e32 v1, 1, v2
	s_nop 0
	v_cndmask_b32_e32 v0, v0, v3, vcc
	v_mul_lo_u32 v2, s84, v0
	v_add_u32_e32 v2, s84, v2
	v_cmp_ne_u32_e32 vcc, v1, v2
	s_and_saveexec_b64 s[4:5], vcc
	s_xor_b64 s[4:5], exec, s[4:5]
	s_cbranch_execz .LBB0_431
	s_movk_i32 s6, 0xd40
	s_lshl_b64 s[6:7], s[6:7], 2
	s_add_u32 s10, s34, s6
	s_addc_u32 s11, s35, s7
	v_mov_b32_e32 v1, 0
	v_mov_b32_e32 v0, 6
	global_load_dword v2, v1, s[10:11] sc1
	s_waitcnt vmcnt(0)
	v_cmp_eq_u32_e32 vcc, v2, v0
	s_and_saveexec_b64 s[6:7], vcc
	s_cbranch_execz .LBB0_430
	s_add_u32 s8, s40, 0x3eaf0200
	s_addc_u32 s9, s41, 0
	s_mov_b32 s26, 1
	s_mov_b64 s[12:13], 0
	s_branch .LBB0_421

; __device__ __forceinline__ unsigned xb_ld(unsigned* p)              { return __hip_atomic_load(p, __ATOMIC_RELAXED, __HIP_MEMORY_SCOPE_AGENT); }
; __device__ __forceinline__ unsigned xb_add(unsigned* p, unsigned v) { return __hip_atomic_fetch_add(p, v, __ATOMIC_RELAXED, __HIP_MEMORY_SCOPE_AGENT); }
; #define XB_SPIN(cond, bar) do { unsigned _sp = 0; while (cond) { __builtin_amdgcn_s_sleep(1); \
;     if ((++_sp & 255u) == 0u) { if (xb_ld(&(bar)[XB_TMO])) break; if (_sp > XB_SPIN_CAP) { atomicAdd(&(bar)[XB_TMO], 1u); break; } } } } while (0)
; __device__ __forceinline__ void xcd_barrier(const XcdBarrier& b, int wv) {
;     ...
;     const unsigned old = xb_add(&bar[XB_XSUB(b.x)], 1u);
;     const unsigned gen = old / b.nloc;
;     if (old + 1u == (gen + 1u) * b.nloc) {
;       __builtin_amdgcn_fence(__ATOMIC_RELEASE, "agent");
;       asm volatile("s_waitcnt vmcnt(0)" ::: "memory");
;       const unsigned og = xb_add(&bar[XB_TOP], 1u);
;       const unsigned tg = og / b.nx;
;       if (og + 1u == (tg + 1u) * b.nx) xb_add(&bar[XB_TOPGEN], 1u);
;       else XB_SPIN(xb_ld(&bar[XB_TOPGEN]) == tg, bar);
;       __builtin_amdgcn_fence(__ATOMIC_ACQUIRE, "agent");
;       xb_add(&bar[XB_XGEN(b.x)], 1u);
;     } else {
;       XB_SPIN(xb_ld(&bar[XB_XGEN(b.x)]) == gen, bar);
.LBB0_785:
	s_or_b64 exec, exec, s[6:7]
	v_cvt_f32_u32_e32 v2, s84
	s_waitcnt vmcnt(0)
	v_readfirstlane_b32 s4, v1
	s_sub_i32 s5, 0, s84
	s_mov_b32 s7, 0
	v_rcp_iflag_f32_e32 v2, v2
	s_nop 0
	v_mul_f32_e32 v1, 0x4f7ffffe, v2
	v_cvt_u32_f32_e32 v1, v1
	v_add_u32_e32 v2, s4, v0
	v_mul_lo_u32 v0, s5, v1
	v_mul_hi_u32 v0, v1, v0
	v_add_u32_e32 v0, v1, v0
	v_mul_hi_u32 v0, v2, v0
	v_mul_lo_u32 v1, v0, s84
	v_sub_u32_e32 v1, v2, v1
	v_add_u32_e32 v3, 1, v0
	v_cmp_le_u32_e32 vcc, s84, v1
	s_nop 1
	v_cndmask_b32_e32 v0, v0, v3, vcc
	v_subrev_u32_e32 v3, s84, v1
	v_cndmask_b32_e32 v1, v1, v3, vcc
	v_add_u32_e32 v3, 1, v0
	v_cmp_le_u32_e32 vcc, s84, v1
	v_add_u32_e32 v1, 1, v2
	s_nop 0
	v_cndmask_b32_e32 v0, v0, v3, vcc
	v_mul_lo_u32 v2, s84, v0
	v_add_u32_e32 v2, s84, v2
	v_cmp_ne_u32_e32 vcc, v1, v2
	s_and_saveexec_b64 s[4:5], vcc
	s_xor_b64 s[4:5], exec, s[4:5]
	s_cbranch_execz .LBB0_799
	s_movk_i32 s6, 0xd40
	s_lshl_b64 s[6:7], s[6:7], 2
	s_add_u32 s10, s34, s6
	s_addc_u32 s11, s35, s7
	v_mov_b32_e32 v1, 0
	v_mov_b32_e32 v0, 7
	global_load_dword v2, v1, s[10:11] sc1
	s_waitcnt vmcnt(0)
	v_cmp_eq_u32_e32 vcc, v2, v0
	s_and_saveexec_b64 s[6:7], vcc
	s_cbranch_execz .LBB0_798
	s_add_u32 s8, s40, 0x3eaf0200
	s_addc_u32 s9, s41, 0
	s_mov_b32 s26, 1
	s_mov_b64 s[12:13], 0
	s_branch .LBB0_789

; __device__ __forceinline__ unsigned xb_ld(unsigned* p)              { return __hip_atomic_load(p, __ATOMIC_RELAXED, __HIP_MEMORY_SCOPE_AGENT); }
; __device__ __forceinline__ unsigned xb_add(unsigned* p, unsigned v) { return __hip_atomic_fetch_add(p, v, __ATOMIC_RELAXED, __HIP_MEMORY_SCOPE_AGENT); }
; #define XB_SPIN(cond, bar) do { unsigned _sp = 0; while (cond) { __builtin_amdgcn_s_sleep(1); \
;     if ((++_sp & 255u) == 0u) { if (xb_ld(&(bar)[XB_TMO])) break; if (_sp > XB_SPIN_CAP) { atomicAdd(&(bar)[XB_TMO], 1u); break; } } } } while (0)
; __device__ __forceinline__ void xcd_barrier(const XcdBarrier& b, int wv) {
;     ...
;     const unsigned old = xb_add(&bar[XB_XSUB(b.x)], 1u);
;     const unsigned gen = old / b.nloc;
;     if (old + 1u == (gen + 1u) * b.nloc) {
;       __builtin_amdgcn_fence(__ATOMIC_RELEASE, "agent");
;       asm volatile("s_waitcnt vmcnt(0)" ::: "memory");
;       const unsigned og = xb_add(&bar[XB_TOP], 1u);
;       const unsigned tg = og / b.nx;
;       if (og + 1u == (tg + 1u) * b.nx) xb_add(&bar[XB_TOPGEN], 1u);
;       else XB_SPIN(xb_ld(&bar[XB_TOPGEN]) == tg, bar);
;       __builtin_amdgcn_fence(__ATOMIC_ACQUIRE, "agent");
;       xb_add(&bar[XB_XGEN(b.x)], 1u);
;     } else {
;       XB_SPIN(xb_ld(&bar[XB_XGEN(b.x)]) == gen, bar);
.LBB0_855:
	s_or_b64 exec, exec, s[6:7]
	v_cvt_f32_u32_e32 v2, s84
	s_waitcnt vmcnt(0)
	v_readfirstlane_b32 s4, v1
	s_sub_i32 s5, 0, s84
	s_mov_b32 s7, 0
	v_rcp_iflag_f32_e32 v2, v2
	s_nop 0
	v_mul_f32_e32 v1, 0x4f7ffffe, v2
	v_cvt_u32_f32_e32 v1, v1
	v_add_u32_e32 v2, s4, v0
	v_mul_lo_u32 v0, s5, v1
	v_mul_hi_u32 v0, v1, v0
	v_add_u32_e32 v0, v1, v0
	v_mul_hi_u32 v0, v2, v0
	v_mul_lo_u32 v1, v0, s84
	v_sub_u32_e32 v1, v2, v1
	v_add_u32_e32 v3, 1, v0
	v_cmp_le_u32_e32 vcc, s84, v1
	s_nop 1
	v_cndmask_b32_e32 v0, v0, v3, vcc
	v_subrev_u32_e32 v3, s84, v1
	v_cndmask_b32_e32 v1, v1, v3, vcc
	v_add_u32_e32 v3, 1, v0
	v_cmp_le_u32_e32 vcc, s84, v1
	v_add_u32_e32 v1, 1, v2
	s_nop 0
	v_cndmask_b32_e32 v0, v0, v3, vcc
	v_mul_lo_u32 v2, s84, v0
	v_add_u32_e32 v2, s84, v2
	v_cmp_ne_u32_e32 vcc, v1, v2
	s_and_saveexec_b64 s[4:5], vcc
	s_xor_b64 s[4:5], exec, s[4:5]
	s_cbranch_execz .LBB0_869
	s_movk_i32 s6, 0xd40
	s_lshl_b64 s[6:7], s[6:7], 2
	s_add_u32 s10, s34, s6
	s_addc_u32 s11, s35, s7
	v_mov_b32_e32 v1, 0
	v_mov_b32_e32 v0, 8
	global_load_dword v2, v1, s[10:11] sc1
	s_waitcnt vmcnt(0)
	v_cmp_eq_u32_e32 vcc, v2, v0
	s_and_saveexec_b64 s[6:7], vcc
	s_cbranch_execz .LBB0_868
	s_add_u32 s8, s40, 0x3eaf0200
	s_addc_u32 s9, s41, 0
	s_mov_b32 s24, 1
	s_mov_b64 s[12:13], 0
	s_branch .LBB0_859

; __device__ __forceinline__ unsigned xb_ld(unsigned* p)              { return __hip_atomic_load(p, __ATOMIC_RELAXED, __HIP_MEMORY_SCOPE_AGENT); }
; __device__ __forceinline__ unsigned xb_add(unsigned* p, unsigned v) { return __hip_atomic_fetch_add(p, v, __ATOMIC_RELAXED, __HIP_MEMORY_SCOPE_AGENT); }
; #define XB_SPIN(cond, bar) do { unsigned _sp = 0; while (cond) { __builtin_amdgcn_s_sleep(1); \
;     if ((++_sp & 255u) == 0u) { if (xb_ld(&(bar)[XB_TMO])) break; if (_sp > XB_SPIN_CAP) { atomicAdd(&(bar)[XB_TMO], 1u); break; } } } } while (0)
; __device__ __forceinline__ void xcd_barrier(const XcdBarrier& b, int wv) {
;     ...
;     const unsigned old = xb_add(&bar[XB_XSUB(b.x)], 1u);
;     const unsigned gen = old / b.nloc;
;     if (old + 1u == (gen + 1u) * b.nloc) {
;       __builtin_amdgcn_fence(__ATOMIC_RELEASE, "agent");
;       asm volatile("s_waitcnt vmcnt(0)" ::: "memory");
;       const unsigned og = xb_add(&bar[XB_TOP], 1u);
;       const unsigned tg = og / b.nx;
;       if (og + 1u == (tg + 1u) * b.nx) xb_add(&bar[XB_TOPGEN], 1u);
;       else XB_SPIN(xb_ld(&bar[XB_TOPGEN]) == tg, bar);
;       __builtin_amdgcn_fence(__ATOMIC_ACQUIRE, "agent");
;       xb_add(&bar[XB_XGEN(b.x)], 1u);
;     } else {
;       XB_SPIN(xb_ld(&bar[XB_XGEN(b.x)]) == gen, bar);
.LBB0_977:
	s_or_b64 exec, exec, s[6:7]
	v_cvt_f32_u32_e32 v2, s84
	s_waitcnt vmcnt(0)
	v_readfirstlane_b32 s4, v1
	s_sub_i32 s5, 0, s84
	s_mov_b32 s7, 0
	v_rcp_iflag_f32_e32 v2, v2
	s_nop 0
	v_mul_f32_e32 v1, 0x4f7ffffe, v2
	v_cvt_u32_f32_e32 v1, v1
	v_add_u32_e32 v2, s4, v0
	v_mul_lo_u32 v0, s5, v1
	v_mul_hi_u32 v0, v1, v0
	v_add_u32_e32 v0, v1, v0
	v_mul_hi_u32 v0, v2, v0
	v_mul_lo_u32 v1, v0, s84
	v_sub_u32_e32 v1, v2, v1
	v_add_u32_e32 v3, 1, v0
	v_cmp_le_u32_e32 vcc, s84, v1
	s_nop 1
	v_cndmask_b32_e32 v0, v0, v3, vcc
	v_subrev_u32_e32 v3, s84, v1
	v_cndmask_b32_e32 v1, v1, v3, vcc
	v_add_u32_e32 v3, 1, v0
	v_cmp_le_u32_e32 vcc, s84, v1
	v_add_u32_e32 v1, 1, v2
	s_nop 0
	v_cndmask_b32_e32 v0, v0, v3, vcc
	v_mul_lo_u32 v2, s84, v0
	v_add_u32_e32 v2, s84, v2
	v_cmp_ne_u32_e32 vcc, v1, v2
	s_and_saveexec_b64 s[4:5], vcc
	s_xor_b64 s[4:5], exec, s[4:5]
	s_cbranch_execz .LBB0_991
	s_movk_i32 s6, 0xd40
	s_lshl_b64 s[6:7], s[6:7], 2
	s_add_u32 s10, s34, s6
	s_addc_u32 s11, s35, s7
	v_mov_b32_e32 v1, 0
	v_mov_b32_e32 v0, 9
	global_load_dword v2, v1, s[10:11] sc1
	s_waitcnt vmcnt(0)
	v_cmp_eq_u32_e32 vcc, v2, v0
	s_and_saveexec_b64 s[6:7], vcc
	s_cbranch_execz .LBB0_990
	s_add_u32 s8, s40, 0x3eaf0200
	s_addc_u32 s9, s41, 0
	s_mov_b32 s24, 1
	s_mov_b64 s[12:13], 0
	s_branch .LBB0_981

; __device__ __forceinline__ unsigned xb_ld(unsigned* p)              { return __hip_atomic_load(p, __ATOMIC_RELAXED, __HIP_MEMORY_SCOPE_AGENT); }
; __device__ __forceinline__ unsigned xb_add(unsigned* p, unsigned v) { return __hip_atomic_fetch_add(p, v, __ATOMIC_RELAXED, __HIP_MEMORY_SCOPE_AGENT); }
; #define XB_SPIN(cond, bar) do { unsigned _sp = 0; while (cond) { __builtin_amdgcn_s_sleep(1); \
;     if ((++_sp & 255u) == 0u) { if (xb_ld(&(bar)[XB_TMO])) break; if (_sp > XB_SPIN_CAP) { atomicAdd(&(bar)[XB_TMO], 1u); break; } } } } while (0)
; __device__ __forceinline__ void xcd_barrier(const XcdBarrier& b, int wv) {
;     ...
;     const unsigned old = xb_add(&bar[XB_XSUB(b.x)], 1u);
;     const unsigned gen = old / b.nloc;
;     if (old + 1u == (gen + 1u) * b.nloc) {
;       __builtin_amdgcn_fence(__ATOMIC_RELEASE, "agent");
;       asm volatile("s_waitcnt vmcnt(0)" ::: "memory");
;       const unsigned og = xb_add(&bar[XB_TOP], 1u);
;       const unsigned tg = og / b.nx;
;       if (og + 1u == (tg + 1u) * b.nx) xb_add(&bar[XB_TOPGEN], 1u);
;       else XB_SPIN(xb_ld(&bar[XB_TOPGEN]) == tg, bar);
;       __builtin_amdgcn_fence(__ATOMIC_ACQUIRE, "agent");
;       xb_add(&bar[XB_XGEN(b.x)], 1u);
;     } else {
;       XB_SPIN(xb_ld(&bar[XB_XGEN(b.x)]) == gen, bar);
.LBB0_1024:
	s_or_b64 exec, exec, s[6:7]
	v_cvt_f32_u32_e32 v2, s84
	s_waitcnt vmcnt(0)
	v_readfirstlane_b32 s4, v1
	s_sub_i32 s5, 0, s84
	s_mov_b32 s7, 0
	v_rcp_iflag_f32_e32 v2, v2
	s_nop 0
	v_mul_f32_e32 v1, 0x4f7ffffe, v2
	v_cvt_u32_f32_e32 v1, v1
	v_add_u32_e32 v2, s4, v0
	v_mul_lo_u32 v0, s5, v1
	v_mul_hi_u32 v0, v1, v0
	v_add_u32_e32 v0, v1, v0
	v_mul_hi_u32 v0, v2, v0
	v_mul_lo_u32 v1, v0, s84
	v_sub_u32_e32 v1, v2, v1
	v_add_u32_e32 v3, 1, v0
	v_cmp_le_u32_e32 vcc, s84, v1
	s_nop 1
	v_cndmask_b32_e32 v0, v0, v3, vcc
	v_subrev_u32_e32 v3, s84, v1
	v_cndmask_b32_e32 v1, v1, v3, vcc
	v_add_u32_e32 v3, 1, v0
	v_cmp_le_u32_e32 vcc, s84, v1
	v_add_u32_e32 v1, 1, v2
	s_nop 0
	v_cndmask_b32_e32 v0, v0, v3, vcc
	v_mul_lo_u32 v2, s84, v0
	v_add_u32_e32 v2, s84, v2
	v_cmp_ne_u32_e32 vcc, v1, v2
	s_and_saveexec_b64 s[4:5], vcc
	s_xor_b64 s[4:5], exec, s[4:5]
	s_cbranch_execz .LBB0_1038
	s_movk_i32 s6, 0xd40
	s_lshl_b64 s[6:7], s[6:7], 2
	s_add_u32 s10, s34, s6
	s_addc_u32 s11, s35, s7
	v_mov_b32_e32 v1, 0
	v_mov_b32_e32 v0, 10
	global_load_dword v2, v1, s[10:11] sc1
	s_waitcnt vmcnt(0)
	v_cmp_eq_u32_e32 vcc, v2, v0
	s_and_saveexec_b64 s[6:7], vcc
	s_cbranch_execz .LBB0_1037
	s_add_u32 s8, s40, 0x3eaf0200
	s_addc_u32 s9, s41, 0
	s_mov_b32 s24, 1
	s_mov_b64 s[12:13], 0
	s_branch .LBB0_1028

; __device__ __forceinline__ unsigned xb_ld(unsigned* p)              { return __hip_atomic_load(p, __ATOMIC_RELAXED, __HIP_MEMORY_SCOPE_AGENT); }
; __device__ __forceinline__ unsigned xb_add(unsigned* p, unsigned v) { return __hip_atomic_fetch_add(p, v, __ATOMIC_RELAXED, __HIP_MEMORY_SCOPE_AGENT); }
; #define XB_SPIN(cond, bar) do { unsigned _sp = 0; while (cond) { __builtin_amdgcn_s_sleep(1); \
;     if ((++_sp & 255u) == 0u) { if (xb_ld(&(bar)[XB_TMO])) break; if (_sp > XB_SPIN_CAP) { atomicAdd(&(bar)[XB_TMO], 1u); break; } } } } while (0)
; __device__ __forceinline__ void xcd_barrier(const XcdBarrier& b, int wv) {
;     ...
;     const unsigned old = xb_add(&bar[XB_XSUB(b.x)], 1u);
;     const unsigned gen = old / b.nloc;
;     if (old + 1u == (gen + 1u) * b.nloc) {
;       __builtin_amdgcn_fence(__ATOMIC_RELEASE, "agent");
;       asm volatile("s_waitcnt vmcnt(0)" ::: "memory");
;       const unsigned og = xb_add(&bar[XB_TOP], 1u);
;       const unsigned tg = og / b.nx;
;       if (og + 1u == (tg + 1u) * b.nx) xb_add(&bar[XB_TOPGEN], 1u);
;       else XB_SPIN(xb_ld(&bar[XB_TOPGEN]) == tg, bar);
;       __builtin_amdgcn_fence(__ATOMIC_ACQUIRE, "agent");
;       xb_add(&bar[XB_XGEN(b.x)], 1u);
;     } else {
;       XB_SPIN(xb_ld(&bar[XB_XGEN(b.x)]) == gen, bar);
.LBB0_1064:
	s_or_b64 exec, exec, s[6:7]
	v_cvt_f32_u32_e32 v2, s84
	s_waitcnt vmcnt(0)
	v_readfirstlane_b32 s4, v1
	s_sub_i32 s5, 0, s84
	s_mov_b32 s7, 0
	v_rcp_iflag_f32_e32 v2, v2
	s_nop 0
	v_mul_f32_e32 v1, 0x4f7ffffe, v2
	v_cvt_u32_f32_e32 v1, v1
	v_add_u32_e32 v2, s4, v0
	v_mul_lo_u32 v0, s5, v1
	v_mul_hi_u32 v0, v1, v0
	v_add_u32_e32 v0, v1, v0
	v_mul_hi_u32 v0, v2, v0
	v_mul_lo_u32 v1, v0, s84
	v_sub_u32_e32 v1, v2, v1
	v_add_u32_e32 v3, 1, v0
	v_cmp_le_u32_e32 vcc, s84, v1
	s_nop 1
	v_cndmask_b32_e32 v0, v0, v3, vcc
	v_subrev_u32_e32 v3, s84, v1
	v_cndmask_b32_e32 v1, v1, v3, vcc
	v_add_u32_e32 v3, 1, v0
	v_cmp_le_u32_e32 vcc, s84, v1
	v_add_u32_e32 v1, 1, v2
	s_nop 0
	v_cndmask_b32_e32 v0, v0, v3, vcc
	v_mul_lo_u32 v2, s84, v0
	v_add_u32_e32 v2, s84, v2
	v_cmp_ne_u32_e32 vcc, v1, v2
	s_and_saveexec_b64 s[4:5], vcc
	s_xor_b64 s[4:5], exec, s[4:5]
	s_cbranch_execz .LBB0_1078
	s_movk_i32 s6, 0xd40
	s_lshl_b64 s[6:7], s[6:7], 2
	s_add_u32 s10, s34, s6
	s_addc_u32 s11, s35, s7
	v_mov_b32_e32 v1, 0
	v_mov_b32_e32 v0, 11
	global_load_dword v2, v1, s[10:11] sc1
	s_waitcnt vmcnt(0)
	v_cmp_eq_u32_e32 vcc, v2, v0
	s_and_saveexec_b64 s[6:7], vcc
	s_cbranch_execz .LBB0_1077
	s_add_u32 s8, s40, 0x3eaf0200
	s_addc_u32 s9, s41, 0
	s_mov_b32 s24, 1
	s_mov_b64 s[12:13], 0
	s_branch .LBB0_1068

; __device__ __forceinline__ unsigned xb_ld(unsigned* p)              { return __hip_atomic_load(p, __ATOMIC_RELAXED, __HIP_MEMORY_SCOPE_AGENT); }
; __device__ __forceinline__ unsigned xb_add(unsigned* p, unsigned v) { return __hip_atomic_fetch_add(p, v, __ATOMIC_RELAXED, __HIP_MEMORY_SCOPE_AGENT); }
; #define XB_SPIN(cond, bar) do { unsigned _sp = 0; while (cond) { __builtin_amdgcn_s_sleep(1); \
;     if ((++_sp & 255u) == 0u) { if (xb_ld(&(bar)[XB_TMO])) break; if (_sp > XB_SPIN_CAP) { atomicAdd(&(bar)[XB_TMO], 1u); break; } } } } while (0)
; __device__ __forceinline__ void xcd_barrier(const XcdBarrier& b, int wv) {
;     ...
;     const unsigned old = xb_add(&bar[XB_XSUB(b.x)], 1u);
;     const unsigned gen = old / b.nloc;
;     if (old + 1u == (gen + 1u) * b.nloc) {
;       __builtin_amdgcn_fence(__ATOMIC_RELEASE, "agent");
;       asm volatile("s_waitcnt vmcnt(0)" ::: "memory");
;       const unsigned og = xb_add(&bar[XB_TOP], 1u);
;       const unsigned tg = og / b.nx;
;       if (og + 1u == (tg + 1u) * b.nx) xb_add(&bar[XB_TOPGEN], 1u);
;       else XB_SPIN(xb_ld(&bar[XB_TOPGEN]) == tg, bar);
;       __builtin_amdgcn_fence(__ATOMIC_ACQUIRE, "agent");
;       xb_add(&bar[XB_XGEN(b.x)], 1u);
;     } else {
;       XB_SPIN(xb_ld(&bar[XB_XGEN(b.x)]) == gen, bar);
.LBB0_1111:
	s_or_b64 exec, exec, s[6:7]
	v_cvt_f32_u32_e32 v2, s84
	s_waitcnt vmcnt(0)
	v_readfirstlane_b32 s4, v1
	s_sub_i32 s5, 0, s84
	s_mov_b32 s7, 0
	v_rcp_iflag_f32_e32 v2, v2
	s_nop 0
	v_mul_f32_e32 v1, 0x4f7ffffe, v2
	v_cvt_u32_f32_e32 v1, v1
	v_add_u32_e32 v2, s4, v0
	v_mul_lo_u32 v0, s5, v1
	v_mul_hi_u32 v0, v1, v0
	v_add_u32_e32 v0, v1, v0
	v_mul_hi_u32 v0, v2, v0
	v_mul_lo_u32 v1, v0, s84
	v_sub_u32_e32 v1, v2, v1
	v_add_u32_e32 v3, 1, v0
	v_cmp_le_u32_e32 vcc, s84, v1
	s_nop 1
	v_cndmask_b32_e32 v0, v0, v3, vcc
	v_subrev_u32_e32 v3, s84, v1
	v_cndmask_b32_e32 v1, v1, v3, vcc
	v_add_u32_e32 v3, 1, v0
	v_cmp_le_u32_e32 vcc, s84, v1
	v_add_u32_e32 v1, 1, v2
	s_nop 0
	v_cndmask_b32_e32 v0, v0, v3, vcc
	v_mul_lo_u32 v2, s84, v0
	v_add_u32_e32 v2, s84, v2
	v_cmp_ne_u32_e32 vcc, v1, v2
	s_and_saveexec_b64 s[4:5], vcc
	s_xor_b64 s[4:5], exec, s[4:5]
	s_cbranch_execz .LBB0_1125
	s_movk_i32 s6, 0xd40
	s_lshl_b64 s[6:7], s[6:7], 2
	s_add_u32 s10, s34, s6
	s_addc_u32 s11, s35, s7
	v_mov_b32_e32 v1, 0
	v_mov_b32_e32 v0, 12
	global_load_dword v2, v1, s[10:11] sc1
	s_waitcnt vmcnt(0)
	v_cmp_eq_u32_e32 vcc, v2, v0
	s_and_saveexec_b64 s[6:7], vcc
	s_cbranch_execz .LBB0_1124
	s_add_u32 s8, s40, 0x3eaf0200
	s_addc_u32 s9, s41, 0
	s_mov_b32 s24, 1
	s_mov_b64 s[12:13], 0
	s_branch .LBB0_1115

; __device__ __forceinline__ unsigned xb_ld(unsigned* p)              { return __hip_atomic_load(p, __ATOMIC_RELAXED, __HIP_MEMORY_SCOPE_AGENT); }
; __device__ __forceinline__ unsigned xb_add(unsigned* p, unsigned v) { return __hip_atomic_fetch_add(p, v, __ATOMIC_RELAXED, __HIP_MEMORY_SCOPE_AGENT); }
; #define XB_SPIN(cond, bar) do { unsigned _sp = 0; while (cond) { __builtin_amdgcn_s_sleep(1); \
;     if ((++_sp & 255u) == 0u) { if (xb_ld(&(bar)[XB_TMO])) break; if (_sp > XB_SPIN_CAP) { atomicAdd(&(bar)[XB_TMO], 1u); break; } } } } while (0)
; __device__ __forceinline__ void xcd_barrier(const XcdBarrier& b, int wv) {
;     ...
;     const unsigned old = xb_add(&bar[XB_XSUB(b.x)], 1u);
;     const unsigned gen = old / b.nloc;
;     if (old + 1u == (gen + 1u) * b.nloc) {
;       __builtin_amdgcn_fence(__ATOMIC_RELEASE, "agent");
;       asm volatile("s_waitcnt vmcnt(0)" ::: "memory");
;       const unsigned og = xb_add(&bar[XB_TOP], 1u);
;       const unsigned tg = og / b.nx;
;       if (og + 1u == (tg + 1u) * b.nx) xb_add(&bar[XB_TOPGEN], 1u);
;       else XB_SPIN(xb_ld(&bar[XB_TOPGEN]) == tg, bar);
;       __builtin_amdgcn_fence(__ATOMIC_ACQUIRE, "agent");
;       xb_add(&bar[XB_XGEN(b.x)], 1u);
;     } else {
;       XB_SPIN(xb_ld(&bar[XB_XGEN(b.x)]) == gen, bar);
.LBB0_1158:
	s_or_b64 exec, exec, s[6:7]
	v_cvt_f32_u32_e32 v2, s84
	s_waitcnt vmcnt(0)
	v_readfirstlane_b32 s4, v1
	s_sub_i32 s5, 0, s84
	s_mov_b32 s7, 0
	v_rcp_iflag_f32_e32 v2, v2
	s_nop 0
	v_mul_f32_e32 v1, 0x4f7ffffe, v2
	v_cvt_u32_f32_e32 v1, v1
	v_add_u32_e32 v2, s4, v0
	v_mul_lo_u32 v0, s5, v1
	v_mul_hi_u32 v0, v1, v0
	v_add_u32_e32 v0, v1, v0
	v_mul_hi_u32 v0, v2, v0
	v_mul_lo_u32 v1, v0, s84
	v_sub_u32_e32 v1, v2, v1
	v_add_u32_e32 v3, 1, v0
	v_cmp_le_u32_e32 vcc, s84, v1
	s_nop 1
	v_cndmask_b32_e32 v0, v0, v3, vcc
	v_subrev_u32_e32 v3, s84, v1
	v_cndmask_b32_e32 v1, v1, v3, vcc
	v_add_u32_e32 v3, 1, v0
	v_cmp_le_u32_e32 vcc, s84, v1
	v_add_u32_e32 v1, 1, v2
	s_nop 0
	v_cndmask_b32_e32 v0, v0, v3, vcc
	v_mul_lo_u32 v2, s84, v0
	v_add_u32_e32 v2, s84, v2
	v_cmp_ne_u32_e32 vcc, v1, v2
	s_and_saveexec_b64 s[4:5], vcc
	s_xor_b64 s[4:5], exec, s[4:5]
	s_cbranch_execz .LBB0_1172
	s_movk_i32 s6, 0xd40
	s_lshl_b64 s[6:7], s[6:7], 2
	s_add_u32 s10, s34, s6
	s_addc_u32 s11, s35, s7
	v_mov_b32_e32 v1, 0
	v_mov_b32_e32 v0, 13
	global_load_dword v2, v1, s[10:11] sc1
	s_waitcnt vmcnt(0)
	v_cmp_eq_u32_e32 vcc, v2, v0
	s_and_saveexec_b64 s[6:7], vcc
	s_cbranch_execz .LBB0_1171
	s_add_u32 s8, s40, 0x3eaf0200
	s_addc_u32 s9, s41, 0
	s_mov_b32 s23, 1
	s_mov_b64 s[12:13], 0
	s_branch .LBB0_1162
